# six-slot scan ring + nt on the scan loop's LDS-DMA loads
# speedup vs baseline: 1.0039x; 1.0039x over previous
.Lsc_pre_cn:
	s_mov_b32 s29, 4
	s_add_i32 s26, s28, s31
	s_mulk_i32 s29, 0x6a00
	s_ashr_i32 s27, s26, 31
	s_add_i32 s38, s29, 0
	s_lshl_b64 s[40:41], s[26:27], 14
	s_add_i32 s29, s38, s30
	v_lshl_add_u64 v[42:43], v[142:143], 0, s[40:41]
	s_mov_b32 m0, s29
	s_and_b64 vcc, exec, s[0:1]
	global_load_lds_dwordx4 v[42:43], off nt
	v_lshl_add_u64 v[42:43], v[144:145], 0, s[40:41]
	s_add_i32 s40, s28, s34
	s_ashr_i32 s41, s40, 31
	s_add_i32 m0, s29, 0x2000
	s_lshl_b64 s[40:41], s[40:41], 15
	global_load_lds_dwordx4 v[42:43], off nt
	v_lshl_add_u64 v[42:43], v[146:147], 0, s[40:41]
	s_add_i32 m0, s29, 0x4000
	s_nop 0
	global_load_lds_dwordx4 v[42:43], off nt
	s_cbranch_vccnz .Lsc_pre_a
	s_lshl_b64 s[40:41], s[26:27], 11
	v_lshl_add_u64 v[42:43], v[148:149], 0, s[40:41]
	s_add_i32 m0, s29, 0x6000
	s_nop 0
	global_load_lds_dwordx4 v[42:43], off nt
.Lsc_pre_a:
	s_and_saveexec_b64 s[28:29], s[20:21]
	s_cbranch_execz .Lsc_pre_g
	s_lshl_b64 s[26:27], s[26:27], 10
	s_add_i32 m0, s38, 0x6800
	v_lshl_add_u64 v[42:43], v[150:151], 0, s[26:27]
	global_load_lds_dwordx4 v[42:43], off nt

.Lsc_cn_done:
	s_and_b32 s38, s35, 0xffff
	s_mul_i32 s38, s38, 0xaaab
	s_lshr_b32 s38, s38, 18
	s_mul_i32 s38, s38, 6
	s_sub_i32 s29, s35, s38
	s_add_i32 s26, s28, s31
	s_mulk_i32 s29, 0x6a00
	s_ashr_i32 s27, s26, 31
	s_add_i32 s38, s29, 0
	s_lshl_b64 s[40:41], s[26:27], 14
	s_add_i32 s29, s38, s30
	v_lshl_add_u64 v[42:43], v[142:143], 0, s[40:41]
	s_mov_b32 m0, s29
	s_and_b64 vcc, exec, s[0:1]
	global_load_lds_dwordx4 v[42:43], off nt
	v_lshl_add_u64 v[42:43], v[144:145], 0, s[40:41]
	s_add_i32 s40, s28, s34
	s_ashr_i32 s41, s40, 31
	s_add_i32 m0, s29, 0x2000
	s_lshl_b64 s[40:41], s[40:41], 15
	global_load_lds_dwordx4 v[42:43], off nt
	v_lshl_add_u64 v[42:43], v[146:147], 0, s[40:41]
	s_add_i32 m0, s29, 0x4000
	s_nop 0
	global_load_lds_dwordx4 v[42:43], off nt
	s_cbranch_vccnz .LBB0_1525
	s_lshl_b64 s[40:41], s[26:27], 11
	v_lshl_add_u64 v[42:43], v[148:149], 0, s[40:41]
	s_add_i32 m0, s29, 0x6000
	s_nop 0
	global_load_lds_dwordx4 v[42:43], off nt
